# baseline (speedup 1.0000x reference)
; DEVI u16 f2bf(float f) { unsigned u = __float_as_uint(f); u += 0x7fffu + ((u >> 16) & 1u); return (u16)(u >> 16); }
; #define MFMA_FENCE() do { __builtin_amdgcn_sched_barrier(0); asm volatile("s_nop 15\n\ts_nop 15" ::: "memory"); __builtin_amdgcn_sched_barrier(0); } while (0)
; DEVI f32x4 mfma16(bf16x8 a, bf16x8 b, f32x4 c) { return __builtin_amdgcn_mfma_f32_16x16x32_bf16(a, b, c, 0, 0, 0); }
; DEVI void ssm_bu16(const u16* Rb, size_t rowg, int g, int lane, const SsmG& G, float* bu) {
;     ...
;   for (int nt = 0; nt < 8; ++nt) {
;     f32x4 d = {0.f, 0.f, 0.f, 0.f};
;     dd[nt] = mfma16(a, G.Bf[nt], d);
;   }
;   MFMA_FENCE();
; #pragma unroll
;   for (int nt = 0; nt < 8; ++nt)
; #pragma unroll
;     for (int r = 0; r < 4; ++r) bu[(quad * 4 + r) * BUS + nt * 16 + l16] = dd[nt][r];
; __device__ __forceinline__ void ssm3_item(KP p, int layer, int b, int c, char* smem, int tix) {
;     ...
;     for (int sc = 0; sc < 4; ++sc) {
;       asm volatile("" ::: "memory");
;       ssm_bu16(Rb, row0 + sc * 16, g, lane, G, bu);
;       asm volatile("" ::: "memory");
; #pragma unroll
;       for (int t = 0; t < 16; ++t) {
;         float br = bu[t * BUS + lane], bi = bu[t * BUS + 64 + lane];
;         float nxr = G.abr * xr - G.abi * xi + br;
;         float nxi = G.abr * xi + G.abi * xr + bi;
;         xr = nxr; xi = nxi;
;         asm volatile("" ::: "memory");
;         u16* xrow = (u16*)(bu + t * BUS);
;         xrow[lane] = f2bf(xr);
;         xrow[64 + lane] = f2bf(xi);
.LBB0_316:
	s_or_b64 exec, exec, s[12:13]
	s_waitcnt vmcnt(0)
	v_mfma_f32_16x16x32_bf16 v[86:89], v[50:53], v[2:5], 0
	v_mfma_f32_16x16x32_bf16 v[90:93], v[50:53], v[10:13], 0
	v_mfma_f32_16x16x32_bf16 v[94:97], v[50:53], v[18:21], 0
	v_mfma_f32_16x16x32_bf16 v[98:101], v[50:53], v[26:29], 0
	v_mfma_f32_16x16x32_bf16 v[102:105], v[50:53], v[6:9], 0
	v_mfma_f32_16x16x32_bf16 v[106:109], v[50:53], v[14:17], 0
	v_mfma_f32_16x16x32_bf16 v[110:113], v[50:53], v[22:25], 0
	v_mfma_f32_16x16x32_bf16 v[50:53], v[50:53], v[30:33], 0
	s_nop 15
	s_nop 15
	v_add_u32_e32 v0, 0x400, v63
	v_add_u32_e32 v77, 0x400, v65
	ds_write2_b32 v63, v86, v90 offset1:16
	ds_write2_b32 v63, v87, v91 offset0:132 offset1:148
	ds_write2_b32 v0, v88, v92 offset0:8 offset1:24
	ds_write2_b32 v0, v89, v93 offset0:140 offset1:156
	ds_write2_b32 v65, v98, v99 offset1:132
	ds_write2_b32 v77, v100, v101 offset0:8 offset1:140
	ds_write2_b32 v63, v94, v102 offset0:32 offset1:64
	ds_write2_b32 v63, v95, v103 offset0:164 offset1:196
	ds_write2_b32 v0, v96, v104 offset0:40 offset1:72
	ds_write2_b32 v0, v97, v105 offset0:172 offset1:204
	ds_write2_b32 v63, v106, v110 offset0:80 offset1:96
	ds_write2_b32 v63, v107, v111 offset0:212 offset1:228
	ds_write2_b32 v0, v108, v112 offset0:88 offset1:104
	ds_write2_b32 v0, v109, v113 offset0:220 offset1:236
	ds_write2_b32 v67, v50, v51 offset1:132
	v_add_u32_e32 v0, 0x400, v67
	ds_write2_b32 v0, v52, v53 offset0:8 offset1:140
	v_add_u32_e32 v53, v128, v127
	ds_read_b32 v194, v126
	ds_read_b32 v195, v53 offset:256
	ds_read_b32 v196, v126 offset:528
	ds_read_b32 v197, v53 offset:784
	ds_read_b32 v198, v126 offset:1056
	ds_read_b32 v199, v53 offset:1312
	ds_read_b32 v200, v126 offset:1584
	ds_read_b32 v201, v53 offset:1840
	ds_read_b32 v202, v126 offset:2112
	ds_read_b32 v203, v53 offset:2368
	ds_read_b32 v204, v126 offset:2640
	ds_read_b32 v205, v53 offset:2896
	ds_read_b32 v206, v126 offset:3168
	ds_read_b32 v207, v53 offset:3424
	s_waitcnt lgkmcnt(6)
	ds_read_b32 v208, v126 offset:3696
	ds_read_b32 v209, v53 offset:3952
	ds_read_b32 v210, v126 offset:4224
	ds_read_b32 v211, v53 offset:4480
	ds_read_b32 v212, v126 offset:4752
	ds_read_b32 v213, v53 offset:5008
	ds_read_b32 v214, v126 offset:5280
	ds_read_b32 v215, v53 offset:5536
	s_waitcnt lgkmcnt(6)
	ds_read_b32 v216, v126 offset:5808
	ds_read_b32 v217, v53 offset:6064
	ds_read_b32 v218, v126 offset:6336
	ds_read_b32 v219, v53 offset:6592
	ds_read_b32 v220, v126 offset:6864
	ds_read_b32 v221, v53 offset:7120
	ds_read_b32 v222, v126 offset:7392
	ds_read_b32 v223, v53 offset:7648
	s_waitcnt lgkmcnt(6)
	ds_read_b32 v224, v126 offset:7920
	ds_read_b32 v225, v53 offset:8176
	s_waitcnt lgkmcnt(0)
	v_mov_b32_e32 v0, v194
	v_mov_b32_e32 v52, v195
	v_pk_mul_f32 v[50:51], v[78:79], v[80:81]
	s_nop 0
	v_sub_f32_e32 v50, v50, v51
	v_add_f32_e32 v0, v50, v0
	v_mul_f32_e32 v50, v82, v80
	v_fmac_f32_e32 v50, v78, v81
	v_bfe_u32 v51, v0, 16, 1
	v_add_f32_e32 v50, v50, v52
	v_add3_u32 v51, v0, v51, s52
	ds_write_b16_d16_hi v128, v51
	v_bfe_u32 v51, v50, 16, 1
	v_add3_u32 v51, v50, v51, s52
	ds_write_b16_d16_hi v128, v51 offset:128
	v_mov_b32_e32 v51, v196
	v_mov_b32_e32 v52, v197
	v_mul_f32_e32 v77, v79, v50
	v_fma_f32 v77, v78, v0, -v77
	v_mul_f32_e32 v50, v78, v50
	v_add_f32_e32 v51, v77, v51
	v_fmac_f32_e32 v50, v79, v0
	v_add_f32_e32 v0, v50, v52
	v_bfe_u32 v50, v51, 16, 1
	v_add3_u32 v50, v51, v50, s52
	ds_write_b16_d16_hi v128, v50 offset:528
	v_bfe_u32 v50, v0, 16, 1
	v_add3_u32 v50, v0, v50, s52
	ds_write_b16_d16_hi v128, v50 offset:656
	v_mov_b32_e32 v50, v198
	v_mov_b32_e32 v52, v199
	v_mul_f32_e32 v77, v79, v0
	v_fma_f32 v77, v78, v51, -v77
	v_mul_f32_e32 v0, v78, v0
	v_add_f32_e32 v50, v77, v50
	v_fmac_f32_e32 v0, v79, v51
	v_bfe_u32 v51, v50, 16, 1
	v_add_f32_e32 v0, v0, v52
	v_add3_u32 v51, v50, v51, s52
	ds_write_b16_d16_hi v128, v51 offset:1056
	v_bfe_u32 v51, v0, 16, 1
	v_add3_u32 v51, v0, v51, s52
	ds_write_b16_d16_hi v128, v51 offset:1184
	v_mov_b32_e32 v51, v200
	v_mov_b32_e32 v52, v201
	v_mul_f32_e32 v77, v79, v0
	v_fma_f32 v77, v78, v50, -v77
	v_mul_f32_e32 v0, v78, v0
	v_add_f32_e32 v51, v77, v51
	v_fmac_f32_e32 v0, v79, v50
	v_bfe_u32 v50, v51, 16, 1
	v_add_f32_e32 v0, v0, v52
	v_add3_u32 v50, v51, v50, s52
	ds_write_b16_d16_hi v128, v50 offset:1584
	v_bfe_u32 v50, v0, 16, 1
	v_add3_u32 v50, v0, v50, s52
	ds_write_b16_d16_hi v128, v50 offset:1712
	v_mov_b32_e32 v50, v202
	v_mov_b32_e32 v52, v203
	v_mul_f32_e32 v77, v79, v0
	v_fma_f32 v77, v78, v51, -v77
	v_mul_f32_e32 v0, v78, v0
	v_add_f32_e32 v50, v77, v50
	v_fmac_f32_e32 v0, v79, v51
	v_bfe_u32 v51, v50, 16, 1
	v_add_f32_e32 v0, v0, v52
	v_add3_u32 v51, v50, v51, s52
	ds_write_b16_d16_hi v128, v51 offset:2112
	v_bfe_u32 v51, v0, 16, 1
	v_add3_u32 v51, v0, v51, s52
	ds_write_b16_d16_hi v128, v51 offset:2240
	v_mov_b32_e32 v51, v204
	v_mov_b32_e32 v52, v205
	v_mul_f32_e32 v77, v79, v0
	v_fma_f32 v77, v78, v50, -v77
	v_mul_f32_e32 v0, v78, v0
	v_add_f32_e32 v51, v77, v51
	v_fmac_f32_e32 v0, v79, v50
	v_bfe_u32 v50, v51, 16, 1
	v_add_f32_e32 v0, v0, v52
	v_add3_u32 v50, v51, v50, s52
	ds_write_b16_d16_hi v128, v50 offset:2640
	v_bfe_u32 v50, v0, 16, 1
	v_add3_u32 v50, v0, v50, s52
	ds_write_b16_d16_hi v128, v50 offset:2768
	v_mov_b32_e32 v50, v206
	v_mov_b32_e32 v52, v207
	v_mul_f32_e32 v77, v79, v0
	v_fma_f32 v77, v78, v51, -v77
	v_mul_f32_e32 v0, v78, v0
	v_add_f32_e32 v50, v77, v50
	v_fmac_f32_e32 v0, v79, v51
	v_bfe_u32 v51, v50, 16, 1
	v_add_f32_e32 v0, v0, v52
	v_add3_u32 v51, v50, v51, s52
	ds_write_b16_d16_hi v128, v51 offset:3168
	v_bfe_u32 v51, v0, 16, 1
	v_add3_u32 v51, v0, v51, s52
	ds_write_b16_d16_hi v128, v51 offset:3296
; DEVI u16 f2bf(float f) { unsigned u = __float_as_uint(f); u += 0x7fffu + ((u >> 16) & 1u); return (u16)(u >> 16); }
; #define MFMA_FENCE() do { __builtin_amdgcn_sched_barrier(0); asm volatile("s_nop 15\n\ts_nop 15" ::: "memory"); __builtin_amdgcn_sched_barrier(0); } while (0)
; DEVI f32x4 mfma16(bf16x8 a, bf16x8 b, f32x4 c) { return __builtin_amdgcn_mfma_f32_16x16x32_bf16(a, b, c, 0, 0, 0); }
; __device__ __forceinline__ void ssm3_item(KP p, int layer, int b, int c, char* smem, int tix) {
;     ...
;       for (int t = 0; t < 16; ++t) {
;         float br = bu[t * BUS + lane], bi = bu[t * BUS + 64 + lane];
;         float nxr = G.abr * xr - G.abi * xi + br;
;         float nxi = G.abr * xi + G.abi * xr + bi;
;         xr = nxr; xi = nxi;
;         asm volatile("" ::: "memory");
;         u16* xrow = (u16*)(bu + t * BUS);
;         xrow[lane] = f2bf(xr);
;         xrow[64 + lane] = f2bf(xi);
;         asm volatile("" ::: "memory");
;       }
;       f32x4 d = {0.f, 0.f, 0.f, 0.f};
; #pragma unroll
;       for (int ks = 0; ks < 4; ++ks) {
;         bf16x8 a = *(const bf16x8*)((const u16*)(bu + l16 * BUS) + ks * 32 + quad * 8);
;         d = mfma16(a, G.Cf[ks], d);
;       }
;       MFMA_FENCE();
	v_mov_b32_e32 v51, v208
	v_mov_b32_e32 v52, v209
	v_mul_f32_e32 v77, v79, v0
	v_fma_f32 v77, v78, v50, -v77
	v_mul_f32_e32 v0, v78, v0
	v_add_f32_e32 v51, v77, v51
	v_fmac_f32_e32 v0, v79, v50
	v_bfe_u32 v50, v51, 16, 1
	v_add_f32_e32 v0, v0, v52
	v_add3_u32 v50, v51, v50, s52
	ds_write_b16_d16_hi v128, v50 offset:3696
	v_bfe_u32 v50, v0, 16, 1
	v_add3_u32 v50, v0, v50, s52
	ds_write_b16_d16_hi v128, v50 offset:3824
	v_mov_b32_e32 v50, v210
	v_mov_b32_e32 v52, v211
	v_mul_f32_e32 v77, v79, v0
	v_fma_f32 v77, v78, v51, -v77
	v_mul_f32_e32 v0, v78, v0
	v_add_f32_e32 v50, v77, v50
	v_fmac_f32_e32 v0, v79, v51
	v_bfe_u32 v51, v50, 16, 1
	v_add_f32_e32 v0, v0, v52
	v_add3_u32 v51, v50, v51, s52
	ds_write_b16_d16_hi v128, v51 offset:4224
	v_bfe_u32 v51, v0, 16, 1
	v_add3_u32 v51, v0, v51, s52
	ds_write_b16_d16_hi v128, v51 offset:4352
	v_mov_b32_e32 v51, v212
	v_mov_b32_e32 v52, v213
	v_mul_f32_e32 v77, v79, v0
	v_fma_f32 v77, v78, v50, -v77
	v_mul_f32_e32 v0, v78, v0
	v_add_f32_e32 v51, v77, v51
	v_fmac_f32_e32 v0, v79, v50
	v_bfe_u32 v50, v51, 16, 1
	v_add_f32_e32 v0, v0, v52
	v_add3_u32 v50, v51, v50, s52
	ds_write_b16_d16_hi v128, v50 offset:4752
	v_bfe_u32 v50, v0, 16, 1
	v_add3_u32 v50, v0, v50, s52
	ds_write_b16_d16_hi v128, v50 offset:4880
	v_mov_b32_e32 v50, v214
	v_mov_b32_e32 v52, v215
	v_mul_f32_e32 v77, v79, v0
	v_fma_f32 v77, v78, v51, -v77
	v_mul_f32_e32 v0, v78, v0
	v_add_f32_e32 v50, v77, v50
	v_fmac_f32_e32 v0, v79, v51
	v_bfe_u32 v51, v50, 16, 1
	v_add_f32_e32 v0, v0, v52
	v_add3_u32 v51, v50, v51, s52
	ds_write_b16_d16_hi v128, v51 offset:5280
	v_bfe_u32 v51, v0, 16, 1
	v_add3_u32 v51, v0, v51, s52
	ds_write_b16_d16_hi v128, v51 offset:5408
	v_mov_b32_e32 v51, v216
	v_mov_b32_e32 v52, v217
	v_mul_f32_e32 v77, v79, v0
	v_fma_f32 v77, v78, v50, -v77
	v_mul_f32_e32 v0, v78, v0
	v_add_f32_e32 v51, v77, v51
	v_fmac_f32_e32 v0, v79, v50
	v_bfe_u32 v50, v51, 16, 1
	v_add_f32_e32 v0, v0, v52
	v_add3_u32 v50, v51, v50, s52
	ds_write_b16_d16_hi v128, v50 offset:5808
	v_bfe_u32 v50, v0, 16, 1
	v_add3_u32 v50, v0, v50, s52
	ds_write_b16_d16_hi v128, v50 offset:5936
	v_mov_b32_e32 v50, v218
	v_mov_b32_e32 v52, v219
	v_mul_f32_e32 v77, v79, v0
	v_fma_f32 v77, v78, v51, -v77
	v_mul_f32_e32 v0, v78, v0
	v_add_f32_e32 v50, v77, v50
	v_fmac_f32_e32 v0, v79, v51
	v_bfe_u32 v51, v50, 16, 1
	v_add_f32_e32 v0, v0, v52
	v_add3_u32 v51, v50, v51, s52
	ds_write_b16_d16_hi v128, v51 offset:6336
	v_bfe_u32 v51, v0, 16, 1
	v_add3_u32 v51, v0, v51, s52
	ds_write_b16_d16_hi v128, v51 offset:6464
	v_mov_b32_e32 v51, v220
	v_mov_b32_e32 v52, v221
	v_mul_f32_e32 v77, v79, v0
	v_fma_f32 v77, v78, v50, -v77
	v_mul_f32_e32 v0, v78, v0
	v_add_f32_e32 v51, v77, v51
	v_fmac_f32_e32 v0, v79, v50
	v_add_f32_e32 v50, v0, v52
	v_bfe_u32 v0, v51, 16, 1
	v_add3_u32 v0, v51, v0, s52
	ds_write_b16_d16_hi v128, v0 offset:6864
	v_bfe_u32 v0, v50, 16, 1
	v_add3_u32 v0, v50, v0, s52
	ds_write_b16_d16_hi v128, v0 offset:6992
	v_mov_b32_e32 v0, v222
	v_mov_b32_e32 v52, v223
	v_mul_f32_e32 v77, v79, v50
	v_fma_f32 v77, v78, v51, -v77
	v_mul_f32_e32 v50, v78, v50
	v_add_f32_e32 v0, v77, v0
	v_fmac_f32_e32 v50, v79, v51
	v_bfe_u32 v51, v0, 16, 1
	v_add_f32_e32 v50, v50, v52
	v_add3_u32 v51, v0, v51, s52
	ds_write_b16_d16_hi v128, v51 offset:7392
	v_bfe_u32 v51, v50, 16, 1
	v_add3_u32 v51, v50, v51, s52
	ds_write_b16_d16_hi v128, v51 offset:7520
	v_mov_b32_e32 v52, v224
	v_mov_b32_e32 v53, v225
	v_pk_mul_f32 v[50:51], v[84:85], v[50:51] op_sel_hi:[1,0]
	s_nop 0
	v_pk_fma_f32 v[80:81], v[78:79], v[0:1], v[50:51] neg_lo:[0,0,1] neg_hi:[0,0,1]
	v_pk_fma_f32 v[50:51], v[78:79], v[0:1], v[50:51] op_sel_hi:[1,0,1]
	s_nop 0
	v_mov_b32_e32 v81, v51
	v_pk_add_f32 v[80:81], v[80:81], v[52:53]
	s_nop 0
	v_bfe_u32 v0, v80, 16, 1
	v_add3_u32 v0, v80, v0, s52
	ds_write_b16_d16_hi v128, v0 offset:7920
	v_bfe_u32 v0, v81, 16, 1
	v_add3_u32 v0, v81, v0, s52
	ds_write_b16_d16_hi v128, v0 offset:8048
	ds_read_b128 v[50:53], v142
	ds_read_b128 v[86:89], v142 offset:64
	s_waitcnt lgkmcnt(1)
	v_mfma_f32_16x16x32_bf16 v[50:53], v[50:53], v[34:37], 0
	ds_read_b128 v[90:93], v142 offset:128
	s_waitcnt lgkmcnt(1)
	v_mfma_f32_16x16x32_bf16 v[50:53], v[86:89], v[38:41], v[50:53]
	ds_read_b128 v[86:89], v142 offset:192
	s_waitcnt lgkmcnt(1)
	v_mfma_f32_16x16x32_bf16 v[50:53], v[90:93], v[42:45], v[50:53]
	s_waitcnt lgkmcnt(0)
	v_mfma_f32_16x16x32_bf16 v[50:53], v[86:89], v[46:49], v[50:53]
	s_nop 15
	s_nop 15
	v_add_u32_e32 v77, s14, v139
	v_add_u32_e32 v0, 0x2040, v77
	v_lshlrev_b64 v[86:87], 13, v[0:1]
	v_lshl_add_u64 v[86:87], s[44:45], 0, v[86:87]
	s_lshl_b64 s[12:13], s[6:7], 1
	v_lshl_add_u64 v[86:87], v[86:87], 0, s[12:13]
	v_lshlrev_b32_e32 v0, 1, v54
	v_lshl_add_u64 v[86:87], v[86:87], 0, v[0:1]
	v_add_co_u32_e32 v86, vcc, s90, v86
	s_add_i32 s14, s14, 16
	s_nop 0
	v_addc_co_u32_e32 v87, vcc, 0, v87, vcc
	global_load_ushort v86, v[86:87], off
	s_cmp_eq_u32 s14, 64
	s_waitcnt vmcnt(0)
; DEVI u16 f2bf(float f) { unsigned u = __float_as_uint(f); u += 0x7fffu + ((u >> 16) & 1u); return (u16)(u >> 16); }
; DEVI float bf2f(u16 h) { return __uint_as_float(((unsigned)h) << 16); }
; DEVI float gelu_tanh(float x) {
;   float u = 0.7978845608028654f * (x + 0.044715f * x * x * x);
;   float e = __expf(2.0f * u);
;   float th = 1.0f - 2.0f / (e + 1.0f);
;   return 0.5f * x * (1.0f + th);
; }
; __device__ __forceinline__ void ssm3_item(KP p, int layer, int b, int c, char* smem, int tix) {
;     ...
; #pragma unroll
;       for (int r = 0; r < 4; ++r) {
;         const int t = sc * 16 + quad * 4 + r;
;         float u = bf2f(Rb[(row0 + t) * RLD + 2048 + g * 16 + l16]);
;         float y = d[r] + G.dsk * u;
;         Gt[t * GT_S + g * 16 + l16] = f2bf(gelu_tanh(y));
;       }
;       asm volatile("" ::: "memory");
	v_lshlrev_b32_e32 v86, 16, v86
	v_fma_f32 v50, v75, v86, v50
	v_mul_f32_e32 v86, 0x3d372713, v50
	v_mul_f32_e32 v86, v50, v86
	v_fma_f32 v86, v50, v86, v50
	v_mul_f32_e32 v86, 0x3f4c422a, v86
	v_add_f32_e32 v86, v86, v86
	v_mul_f32_e32 v86, 0x3fb8aa3b, v86
	v_exp_f32_e32 v86, v86
	v_mul_f32_e32 v50, 0.5, v50
	v_add_f32_e32 v86, 1.0, v86
	v_div_scale_f32 v87, s[22:23], v86, v86, 2.0
	v_rcp_f32_e32 v88, v87
	s_nop 0
	v_fma_f32 v89, -v87, v88, 1.0
	v_fmac_f32_e32 v88, v89, v88
	v_div_scale_f32 v89, vcc, 2.0, v86, 2.0
	v_mul_f32_e32 v90, v89, v88
	v_fma_f32 v91, -v87, v90, v89
	v_fmac_f32_e32 v90, v91, v88
	v_fma_f32 v87, -v87, v90, v89
	v_div_fmas_f32 v87, v87, v88, v90
	v_div_fixup_f32 v86, v87, v86, 2.0
	v_sub_f32_e32 v86, 1.0, v86
	v_add_f32_e32 v86, 1.0, v86
	v_mul_f32_e32 v50, v50, v86
	v_bfe_u32 v86, v50, 16, 1
	v_add3_u32 v50, v50, v86, s52
	v_add_u32_e32 v86, 0x2041, v77
	v_mov_b32_e32 v87, v1
	v_lshlrev_b64 v[86:87], 13, v[86:87]
	v_lshl_add_u64 v[86:87], s[44:45], 0, v[86:87]
	v_lshl_add_u64 v[86:87], v[86:87], 0, s[12:13]
	v_lshl_add_u64 v[86:87], v[86:87], 0, v[0:1]
	v_add_co_u32_e32 v86, vcc, s90, v86
	ds_write_b16_d16_hi v83, v50
	s_nop 0
	v_addc_co_u32_e32 v87, vcc, 0, v87, vcc
	global_load_ushort v50, v[86:87], off
	s_waitcnt vmcnt(0)
	v_lshlrev_b32_e32 v50, 16, v50
	v_fma_f32 v50, v75, v50, v51
	v_mul_f32_e32 v51, 0x3d372713, v50
	v_mul_f32_e32 v51, v50, v51
	v_fma_f32 v51, v50, v51, v50
	v_mul_f32_e32 v51, 0x3f4c422a, v51
	v_add_f32_e32 v51, v51, v51
	v_mul_f32_e32 v51, 0x3fb8aa3b, v51
	v_exp_f32_e32 v51, v51
	v_mul_f32_e32 v50, 0.5, v50
	v_add_f32_e32 v51, 1.0, v51
	v_div_scale_f32 v86, s[22:23], v51, v51, 2.0
	v_rcp_f32_e32 v87, v86
	s_nop 0
	v_fma_f32 v88, -v86, v87, 1.0
	v_fmac_f32_e32 v87, v88, v87
	v_div_scale_f32 v88, vcc, 2.0, v51, 2.0
	v_mul_f32_e32 v89, v88, v87
	v_fma_f32 v90, -v86, v89, v88
	v_fmac_f32_e32 v89, v90, v87
	v_fma_f32 v86, -v86, v89, v88
	v_div_fmas_f32 v86, v86, v87, v89
	v_div_fixup_f32 v51, v86, v51, 2.0
	v_sub_f32_e32 v51, 1.0, v51
	v_add_f32_e32 v51, 1.0, v51
	v_mul_f32_e32 v50, v50, v51
	v_bfe_u32 v51, v50, 16, 1
	v_add3_u32 v50, v50, v51, s52
	ds_write_b16_d16_hi v83, v50 offset:1040
	v_add_u32_e32 v50, 0x2042, v77
	v_mov_b32_e32 v51, v1
	v_lshlrev_b64 v[50:51], 13, v[50:51]
	v_lshl_add_u64 v[50:51], s[44:45], 0, v[50:51]
	v_lshl_add_u64 v[50:51], v[50:51], 0, s[12:13]
	v_lshl_add_u64 v[50:51], v[50:51], 0, v[0:1]
	v_add_co_u32_e32 v50, vcc, s90, v50
	s_nop 1
	v_addc_co_u32_e32 v51, vcc, 0, v51, vcc
	global_load_ushort v50, v[50:51], off
	s_waitcnt vmcnt(0)
	v_lshlrev_b32_e32 v50, 16, v50
	v_fma_f32 v50, v75, v50, v52
	v_mul_f32_e32 v51, 0x3d372713, v50
	v_mul_f32_e32 v51, v50, v51
	v_fma_f32 v51, v50, v51, v50
	v_mul_f32_e32 v51, 0x3f4c422a, v51
	v_add_f32_e32 v51, v51, v51
	v_mul_f32_e32 v51, 0x3fb8aa3b, v51
	v_exp_f32_e32 v51, v51
	v_mul_f32_e32 v50, 0.5, v50
	v_add_f32_e32 v51, 1.0, v51
	v_div_scale_f32 v52, s[22:23], v51, v51, 2.0
	v_rcp_f32_e32 v86, v52
	s_nop 0
	v_fma_f32 v87, -v52, v86, 1.0
	v_fmac_f32_e32 v86, v87, v86
	v_div_scale_f32 v87, vcc, 2.0, v51, 2.0
	v_mul_f32_e32 v88, v87, v86
	v_fma_f32 v89, -v52, v88, v87
	v_fmac_f32_e32 v88, v89, v86
	v_fma_f32 v52, -v52, v88, v87
	v_div_fmas_f32 v52, v52, v86, v88
	v_div_fixup_f32 v51, v52, v51, 2.0
	v_sub_f32_e32 v51, 1.0, v51
	v_add_f32_e32 v51, 1.0, v51
	v_mul_f32_e32 v50, v50, v51
	v_bfe_u32 v51, v50, 16, 1
	v_add3_u32 v50, v50, v51, s52
	ds_write_b16_d16_hi v83, v50 offset:2080
	v_add_u32_e32 v50, 0x2043, v77
	v_mov_b32_e32 v51, v1
	v_lshlrev_b64 v[50:51], 13, v[50:51]
	v_lshl_add_u64 v[50:51], s[44:45], 0, v[50:51]
	v_lshl_add_u64 v[50:51], v[50:51], 0, s[12:13]
	v_lshl_add_u64 v[50:51], v[50:51], 0, v[0:1]
	v_add_co_u32_e32 v50, vcc, s90, v50
	s_nop 1
	v_addc_co_u32_e32 v51, vcc, 0, v51, vcc
	global_load_ushort v0, v[50:51], off
	s_waitcnt vmcnt(0)
	v_lshlrev_b32_e32 v0, 16, v0
	v_fmac_f32_e32 v53, v75, v0
	v_mul_f32_e32 v0, 0x3d372713, v53
	v_mul_f32_e32 v0, v53, v0
	v_fma_f32 v0, v53, v0, v53
	v_mul_f32_e32 v0, 0x3f4c422a, v0
	v_add_f32_e32 v0, v0, v0
	v_mul_f32_e32 v0, 0x3fb8aa3b, v0
	v_exp_f32_e32 v0, v0
	s_nop 0
	v_add_f32_e32 v0, 1.0, v0
	v_div_scale_f32 v50, s[12:13], v0, v0, 2.0
	v_rcp_f32_e32 v51, v50
	s_nop 0
	v_fma_f32 v52, -v50, v51, 1.0
	v_fmac_f32_e32 v51, v52, v51
	v_div_scale_f32 v52, vcc, 2.0, v0, 2.0
	v_mul_f32_e32 v77, v52, v51
	v_fma_f32 v86, -v50, v77, v52
	v_fmac_f32_e32 v77, v86, v51
	v_fma_f32 v50, -v50, v77, v52
	v_div_fmas_f32 v50, v50, v51, v77
	v_div_fixup_f32 v0, v50, v0, 2.0
	v_sub_f32_e32 v0, 1.0, v0
	v_mul_f32_e32 v50, 0.5, v53
	v_add_f32_e32 v0, 1.0, v0
	v_mul_f32_e32 v0, v50, v0
	v_bfe_u32 v50, v0, 16, 1
	v_add3_u32 v0, v0, v50, s52
	ds_write_b16_d16_hi v83, v0 offset:3120
	v_add_u32_e32 v83, 0x4100, v83
	s_cbranch_scc1 .LBB0_274
